# phase-0 x f32->f16 conversion loop software-pipelined (next iteration loads in flight during convert/store)
# baseline (speedup 1.0000x reference)
; __device__ __forceinline__ void cvt_pass(const float* src, h16* dst, size_t n, float* dup) {
;     for (size_t i = ((size_t)blockIdx.x * 512 + threadIdx.x) * 8; i < n; i += (size_t)gridDim.x * 512 * 8) {
;         const f32x4 a = *(const f32x4*)(src + i), b = *(const f32x4*)(src + i + 4);
;         h16x8 o; o[0] = (h16)a.x; o[1] = (h16)a.y; o[2] = (h16)a.z; o[3] = (h16)a.w; o[4] = (h16)b.x; o[5] = (h16)b.y; o[6] = (h16)b.z; o[7] = (h16)b.w;
;         *(h16x8*)(dst + i) = o;
;         if (dup) { *(f32x4*)(dup + i) = a; *(f32x4*)(dup + i + 4) = b; }
;     }
; }
.Lcv_loop:
	s_mov_b64 s[18:19], exec
	v_lshl_add_u64 v[10:11], v[10:11], 0, s[10:11]
	v_cmp_lt_u64_e32 vcc, s[16:17], v[10:11]
	v_lshl_add_u64 v[6:7], v[6:7], 0, s[12:13]
	s_or_b64 s[14:15], vcc, s[14:15]
	s_andn2_b64 exec, s[18:19], s[14:15]
	s_cbranch_execz .Lcv_last0
	global_load_dwordx4 v[20:23], v[6:7], off
	global_load_dwordx4 v[24:27], v[6:7], off offset:-16
	s_mov_b64 exec, s[18:19]
	s_waitcnt vmcnt(2)
	v_cvt_pk_f16_f32 v15, v14, v15
	v_cvt_pk_f16_f32 v14, v12, v13
	v_cvt_pk_f16_f32 v13, v18, v19
	v_cvt_pk_f16_f32 v12, v16, v17
	global_store_dwordx4 v[8:9], v[12:15], off
	v_lshl_add_u64 v[8:9], v[8:9], 0, s[4:5]
	s_andn2_b64 exec, exec, s[14:15]
	s_mov_b64 s[18:19], exec
	v_lshl_add_u64 v[10:11], v[10:11], 0, s[10:11]
	v_cmp_lt_u64_e32 vcc, s[16:17], v[10:11]
	v_lshl_add_u64 v[6:7], v[6:7], 0, s[12:13]
	s_or_b64 s[14:15], vcc, s[14:15]
	s_andn2_b64 exec, s[18:19], s[14:15]
	s_cbranch_execz .Lcv_last1
	global_load_dwordx4 v[12:15], v[6:7], off
	global_load_dwordx4 v[16:19], v[6:7], off offset:-16
	s_mov_b64 exec, s[18:19]
	s_waitcnt vmcnt(2)
	v_cvt_pk_f16_f32 v23, v22, v23
	v_cvt_pk_f16_f32 v22, v20, v21
	v_cvt_pk_f16_f32 v21, v26, v27
	v_cvt_pk_f16_f32 v20, v24, v25
	global_store_dwordx4 v[8:9], v[20:23], off
	v_lshl_add_u64 v[8:9], v[8:9], 0, s[4:5]
	s_andn2_b64 exec, exec, s[14:15]
	s_branch .Lcv_loop
.Lcv_last0:
	s_mov_b64 exec, s[18:19]
	s_waitcnt vmcnt(0)
	v_cvt_pk_f16_f32 v15, v14, v15
	v_cvt_pk_f16_f32 v14, v12, v13
	v_cvt_pk_f16_f32 v13, v18, v19
	v_cvt_pk_f16_f32 v12, v16, v17
	global_store_dwordx4 v[8:9], v[12:15], off
	v_lshl_add_u64 v[8:9], v[8:9], 0, s[4:5]
	s_branch .LBB0_114
.Lcv_last1:
	s_mov_b64 exec, s[18:19]
	s_waitcnt vmcnt(0)
	v_cvt_pk_f16_f32 v23, v22, v23
	v_cvt_pk_f16_f32 v22, v20, v21
	v_cvt_pk_f16_f32 v21, v26, v27
	v_cvt_pk_f16_f32 v20, v24, v25
	global_store_dwordx4 v[8:9], v[20:23], off
	v_lshl_add_u64 v[8:9], v[8:9], 0, s[4:5]
